# early L2 write-back by arrivers 12 and 24 of each XCD (instead of 16 only)
# speedup vs baseline: 1.0134x; 1.0098x over previous
.LBB0_140:
	s_or_b64 exec, exec, s[8:9]
	v_cvt_f32_u32_e32 v4, v2
	s_waitcnt vmcnt(0)
	v_readfirstlane_b32 s3, v3
	v_sub_u32_e32 v3, 0, v2
	v_rcp_iflag_f32_e32 v4, v4
	v_add_u32_e32 v5, s3, v1
	v_mul_f32_e32 v4, 0x4f7ffffe, v4
	v_cvt_u32_f32_e32 v4, v4
	v_mul_lo_u32 v1, v3, v4
	v_mul_hi_u32 v1, v4, v1
	v_add_u32_e32 v1, v4, v1
	v_mul_hi_u32 v1, v5, v1
	v_mul_lo_u32 v3, v1, v2
	v_sub_u32_e32 v3, v5, v3
	v_add_u32_e32 v4, 1, v1
	v_cmp_ge_u32_e32 vcc, v3, v2
	s_nop 1
	v_cndmask_b32_e32 v1, v1, v4, vcc
	v_sub_u32_e32 v4, v3, v2
	v_cndmask_b32_e32 v3, v3, v4, vcc
	v_add_u32_e32 v4, 1, v1
	v_cmp_ge_u32_e32 vcc, v3, v2
	v_add_u32_e32 v3, 1, v5
	s_nop 0
	v_cndmask_b32_e32 v1, v1, v4, vcc
	v_mul_lo_u32 v4, v2, v1
	v_add_u32_e32 v2, v4, v2
	v_cmp_ne_u32_e32 vcc, v3, v2
	s_and_saveexec_b64 s[6:7], vcc
	s_xor_b64 s[6:7], exec, s[6:7]
	s_cbranch_execz .LBB0_154
	s_waitcnt lgkmcnt(0)
	v_mov_b32_e32 v0, 0x2000
	buffer_inv sc1
	v_readfirstlane_b32 s12, v5
	s_and_b32 s12, s12, 31
	s_cmp_eq_u32 s12, 12
	s_cbranch_scc1 .Lewb_do1
	s_cmp_eq_u32 s12, 24
	s_cbranch_scc0 .Lewb_skip1
.Lewb_do1:
	buffer_wbl2 sc1

.LBB0_939:
	s_or_b64 exec, exec, s[16:17]
	v_cvt_f32_u32_e32 v4, v2
	s_waitcnt vmcnt(0)
	v_readfirstlane_b32 s2, v3
	v_sub_u32_e32 v3, 0, v2
	v_rcp_iflag_f32_e32 v4, v4
	v_add_u32_e32 v5, s2, v1
	v_mul_f32_e32 v4, 0x4f7ffffe, v4
	v_cvt_u32_f32_e32 v4, v4
	v_mul_lo_u32 v1, v3, v4
	v_mul_hi_u32 v1, v4, v1
	v_add_u32_e32 v1, v4, v1
	v_mul_hi_u32 v1, v5, v1
	v_mul_lo_u32 v3, v1, v2
	v_sub_u32_e32 v3, v5, v3
	v_add_u32_e32 v4, 1, v1
	v_cmp_ge_u32_e32 vcc, v3, v2
	s_nop 1
	v_cndmask_b32_e32 v1, v1, v4, vcc
	v_sub_u32_e32 v4, v3, v2
	v_cndmask_b32_e32 v3, v3, v4, vcc
	v_add_u32_e32 v4, 1, v1
	v_cmp_ge_u32_e32 vcc, v3, v2
	v_add_u32_e32 v3, 1, v5
	s_nop 0
	v_cndmask_b32_e32 v1, v1, v4, vcc
	v_mul_lo_u32 v4, v2, v1
	v_add_u32_e32 v2, v4, v2
	v_cmp_ne_u32_e32 vcc, v3, v2
	s_and_saveexec_b64 s[8:9], vcc
	s_xor_b64 s[14:15], exec, s[8:9]
	s_cbranch_execz .LBB0_953
	s_waitcnt lgkmcnt(0)
	buffer_inv sc1
	v_readfirstlane_b32 s18, v5
	s_and_b32 s18, s18, 31
	s_cmp_eq_u32 s18, 12
	s_cbranch_scc1 .Lewb_do2
	s_cmp_eq_u32 s18, 24
	s_cbranch_scc0 .Lewb_skip2

.LBB0_1593:
	s_or_b64 exec, exec, s[18:19]
	v_cvt_f32_u32_e32 v4, v2
	s_waitcnt vmcnt(0)
	v_readfirstlane_b32 s2, v3
	v_sub_u32_e32 v3, 0, v2
	v_rcp_iflag_f32_e32 v4, v4
	v_add_u32_e32 v5, s2, v1
	v_mul_f32_e32 v4, 0x4f7ffffe, v4
	v_cvt_u32_f32_e32 v4, v4
	v_mul_lo_u32 v1, v3, v4
	v_mul_hi_u32 v1, v4, v1
	v_add_u32_e32 v1, v4, v1
	v_mul_hi_u32 v1, v5, v1
	v_mul_lo_u32 v3, v1, v2
	v_sub_u32_e32 v3, v5, v3
	v_add_u32_e32 v4, 1, v1
	v_cmp_ge_u32_e32 vcc, v3, v2
	s_nop 1
	v_cndmask_b32_e32 v1, v1, v4, vcc
	v_sub_u32_e32 v4, v3, v2
	v_cndmask_b32_e32 v3, v3, v4, vcc
	v_add_u32_e32 v4, 1, v1
	v_cmp_ge_u32_e32 vcc, v3, v2
	v_add_u32_e32 v3, 1, v5
	s_nop 0
	v_cndmask_b32_e32 v1, v1, v4, vcc
	v_mul_lo_u32 v4, v2, v1
	v_add_u32_e32 v2, v4, v2
	v_cmp_ne_u32_e32 vcc, v3, v2
	s_and_saveexec_b64 s[8:9], vcc
	s_xor_b64 s[16:17], exec, s[8:9]
	s_cbranch_execz .LBB0_1607
	s_waitcnt lgkmcnt(0)
	buffer_inv sc1
	v_readfirstlane_b32 s20, v5
	s_and_b32 s20, s20, 31
	s_cmp_eq_u32 s20, 12
	s_cbranch_scc1 .Lewb_do5
	s_cmp_eq_u32 s20, 24
	s_cbranch_scc0 .Lewb_skip5

.LBB0_1713:
	s_or_b64 exec, exec, s[16:17]
	v_cvt_f32_u32_e32 v4, v2
	s_waitcnt vmcnt(0)
	v_readfirstlane_b32 s8, v3
	v_sub_u32_e32 v3, 0, v2
	v_rcp_iflag_f32_e32 v4, v4
	v_add_u32_e32 v5, s8, v1
	v_mul_f32_e32 v4, 0x4f7ffffe, v4
	v_cvt_u32_f32_e32 v4, v4
	v_mul_lo_u32 v1, v3, v4
	v_mul_hi_u32 v1, v4, v1
	v_add_u32_e32 v1, v4, v1
	v_mul_hi_u32 v1, v5, v1
	v_mul_lo_u32 v3, v1, v2
	v_sub_u32_e32 v3, v5, v3
	v_add_u32_e32 v4, 1, v1
	v_cmp_ge_u32_e32 vcc, v3, v2
	s_nop 1
	v_cndmask_b32_e32 v1, v1, v4, vcc
	v_sub_u32_e32 v4, v3, v2
	v_cndmask_b32_e32 v3, v3, v4, vcc
	v_add_u32_e32 v4, 1, v1
	v_cmp_ge_u32_e32 vcc, v3, v2
	v_add_u32_e32 v3, 1, v5
	s_nop 0
	v_cndmask_b32_e32 v1, v1, v4, vcc
	v_mul_lo_u32 v4, v2, v1
	v_add_u32_e32 v2, v4, v2
	v_cmp_ne_u32_e32 vcc, v3, v2
	s_and_saveexec_b64 s[8:9], vcc
	s_xor_b64 s[14:15], exec, s[8:9]
	s_cbranch_execz .LBB0_1727
	s_waitcnt lgkmcnt(0)
	buffer_inv sc1
	v_readfirstlane_b32 s18, v5
	s_and_b32 s18, s18, 31
	s_cmp_eq_u32 s18, 12
	s_cbranch_scc1 .Lewb_do6
	s_cmp_eq_u32 s18, 24
	s_cbranch_scc0 .Lewb_skip6
